# stack18 + prologue LoRA weight image loop rewritten by hand: eight rows loaded together under one exec mask from a wave-uniform scalar base, one wait, one 16-byte store (was ~24 serial s_load/global-l
# speedup vs baseline: 1.0116x; 1.0116x over previous
; #define GAS __attribute__((address_space(1)))
; __device__ __forceinline__ unsigned pk2(float lo, float hi) { return pg8::cvt_pk_bf16(lo, hi); }
; #define INP(k) (*(const float* const __attribute__((address_space(4)))*)(ka + 8 * (k)))
; __device__ __forceinline__ void phase_prologue(Frame& F) {
;     ...
;     const int gt = (F.vcu * NWAVES + F.wave) * 64 + lane, NGT = NGW * 64;
;     for (int it = gt; it < NL * 3072 * 32; it += NGT) {
;         const int l = it / (3072 * 32), rr = it % (3072 * 32), n = rr >> 5, k0 = (rr & 31) * 8;
;         float v[8];
; #pragma unroll
;         for (int j = 0; j < 8; ++j) { const int k = k0 + j; float x = 0.f;
;             if (n < 1024) { if (k < 64) x = ((const GAS float*)INP(10))[((size_t)l * 64 + k) * 1024 + n]; }
;             else if (n < 2048) { if (k >= 64 && k < 128) x = ((const GAS float*)INP(12))[((size_t)l * 64 + (k - 64)) * 1024 + (n - 1024)]; }
;             else { if (k >= 128) x = ((const GAS float*)INP(13))[((size_t)l * 128 + (k - 128)) * 1024 + (n - 2048)]; }
;             v[j] = x; }
;         v4u o; o.x = pk2(v[0], v[1]); o.y = pk2(v[2], v[3]); o.z = pk2(v[4], v[5]); o.w = pk2(v[6], v[7]);
;         *(GAS v4u*)((bf16*)(ws_ + WS_WLORA + l * SZ_WLORA) + (size_t)n * 256 + k0) = o;
;     }
.LBB0_55:
	s_lshl_b32 s1, s37, 9
	s_and_b32 s0, s36, 0xffffffc0
	s_add_i32 s1, s1, s0
	v_add_u32_e32 v12, s1, v37
	s_mov_b32 s1, 0x60000
	v_writelane_b32 v254, s0, 14
	v_cmp_gt_i32_e32 vcc, s1, v12
	s_and_saveexec_b64 s[12:13], vcc
	s_cbranch_execz .LBB0_170
	s_load_dwordx2 s[16:17], s[10:11], 0x50
	s_load_dwordx2 s[18:19], s[10:11], 0x60
	s_load_dwordx2 s[20:21], s[10:11], 0x68
	s_add_u32 s14, s4, 0x1e500000
	s_addc_u32 s15, s5, 0
	s_lshl_b32 s3, s33, 9
	v_mov_b32_e32 v1, 0
	s_waitcnt lgkmcnt(0)
.Llora_loop:
	v_lshrrev_b32_e32 v13, 15, v12
	v_mul_u32_u24_e32 v13, 0xaaab, v13
	v_lshrrev_b32_e32 v13, 17, v13
	v_mul_u32_u24_e32 v14, 0x18000, v13
	v_sub_u32_e32 v14, v12, v14
	v_lshrrev_b32_e32 v15, 5, v14
	v_and_b32_e32 v16, 31, v14
	v_lshlrev_b32_e32 v16, 3, v16
	v_readfirstlane_b32 s22, v13
	v_readfirstlane_b32 s23, v15
	s_lshr_b32 s23, s23, 10
	s_cmp_eq_u32 s23, 2
	s_cselect_b32 s24, 0x80, 64
	s_lshl_b32 s25, s23, 6
	s_cmp_eq_u32 s23, 0
	s_cselect_b32 s26, s16, s18
	s_cselect_b32 s27, s17, s19
	s_cmp_eq_u32 s23, 2
	s_cselect_b32 s26, s20, s26
	s_cselect_b32 s27, s21, s27
	s_mul_i32 s28, s22, s24
	v_subrev_u32_e32 v17, s25, v16
	v_cmp_gt_u32_e32 vcc, s24, v17
	v_add_u32_e32 v18, s28, v17
	v_and_b32_e32 v19, 0x3ff, v15
	v_lshlrev_b32_e32 v19, 2, v19
	v_lshl_add_u32 v18, v18, 12, v19
	v_mov_b32_e32 v20, 0
	v_mov_b32_e32 v21, 0
	v_mov_b32_e32 v22, 0
	v_mov_b32_e32 v23, 0
	v_mov_b32_e32 v24, 0
	v_mov_b32_e32 v25, 0
	v_mov_b32_e32 v26, 0
	v_mov_b32_e32 v27, 0
	s_and_saveexec_b64 s[30:31], vcc
	global_load_dword v20, v18, s[26:27]
	s_add_u32 s26, s26, 0x1000
	s_addc_u32 s27, s27, 0
	global_load_dword v21, v18, s[26:27]
	s_add_u32 s26, s26, 0x1000
	s_addc_u32 s27, s27, 0
	global_load_dword v22, v18, s[26:27]
	s_add_u32 s26, s26, 0x1000
	s_addc_u32 s27, s27, 0
	global_load_dword v23, v18, s[26:27]
	s_add_u32 s26, s26, 0x1000
	s_addc_u32 s27, s27, 0
	global_load_dword v24, v18, s[26:27]
	s_add_u32 s26, s26, 0x1000
	s_addc_u32 s27, s27, 0
	global_load_dword v25, v18, s[26:27]
	s_add_u32 s26, s26, 0x1000
	s_addc_u32 s27, s27, 0
	global_load_dword v26, v18, s[26:27]
	s_add_u32 s26, s26, 0x1000
	s_addc_u32 s27, s27, 0
	global_load_dword v27, v18, s[26:27]
	s_or_b64 exec, exec, s[30:31]
	s_mul_i32 s28, s22, 0x180000
	s_add_u32 s28, s14, s28
	s_addc_u32 s29, s15, 0
	v_lshlrev_b32_e32 v28, 9, v15
	v_lshl_add_u32 v28, v16, 1, v28
	s_waitcnt vmcnt(0)
	v_cvt_pk_bf16_f32 v20, v20, v21
	v_cvt_pk_bf16_f32 v21, v22, v23
	v_cvt_pk_bf16_f32 v22, v24, v25
	v_cvt_pk_bf16_f32 v23, v26, v27
	global_store_dwordx4 v28, v[20:23], s[28:29]
	v_add_u32_e32 v12, s3, v12
	v_cmp_gt_i32_e32 vcc, 0x60000, v12
	s_and_b64 exec, exec, vcc
	s_cbranch_execnz .Llora_loop
